# PROJ: the quarter-cost pad tiles go first to the second-half workgroups so the two workgroups of a CU run their epilogues out of phase
# baseline (speedup 1.0000x reference)
.LBB0_448:
	s_or_b64 exec, exec, s[20:21]
	s_add_i32 s43, s43, s38
	s_add_i32 s42, s42, s39
	s_and_b32 s36, s43, 32
	s_lshl_b32 s36, s36, 1
	s_add_u32 s36, s36, 0x17f
	s_cmp_gt_u32 s43, s36
	s_cbranch_scc1 .LBB0_709
.LBB0_449:
	s_and_b32 s36, s43, 32
	s_cmp_eq_u32 s36, 0
	s_cbranch_scc1 .Lproj_e0
	s_cmp_lt_u32 s43, 64
	s_cbranch_scc0 .Lproj_e1
	s_add_u32 s37, s43, 0x160
	s_branch .Lproj_e2
.Lproj_e1:
	s_sub_u32 s37, s43, 64
	s_branch .Lproj_e2
.Lproj_e0:
	s_mov_b32 s37, s43
.Lproj_e2:
	s_cmpk_lt_u32 s37, 0x180
	s_cbranch_scc0 .Lproj_ci
	s_mul_i32 s4, s37, 0x2ab
	s_lshr_b32 s4, s4, 16
	s_mul_i32 s5, s4, 0x60
	s_lshl_b32 s6, s4, 6
	s_lshl_b32 s4, s37, 3
	s_and_b32 s4, s4, 56
	s_or_b32 s16, s4, s6
	s_sub_i32 s5, s37, s5
	s_lshl_b32 s5, s5, 5
	s_and_b32 s17, s5, 0xf00
	s_branch .Lproj_cd
.Lproj_ci:
	s_sub_u32 s16, s37, 0x180
	s_lshl_b32 s16, s16, 3
	s_movk_i32 s17, 0xc00
	s_mov_b32 s6, s16
.Lproj_cd:
	s_or_b32 s4, s16, s67
	v_mov_b32 v10, v198
	v_ashrrev_i32_e32 v0, 2, v10
	s_lshl_b32 s4, s4, 7
	v_add_u32_e32 v2, s4, v0
	v_ashrrev_i32_e32 v3, 31, v2
	v_lshlrev_b64 v[2:3], 11, v[2:3]
	v_lshlrev_b32_e32 v1, 4, v10
	v_add_u32_e32 v4, s17, v0
	v_lshl_add_u64 v[2:3], s[96:97], 0, v[2:3]
	v_and_b32_e32 v152, 48, v1
	v_ashrrev_i32_e32 v5, 31, v4
	v_lshl_add_u64 v[2:3], v[2:3], 0, v[152:153]
	v_lshlrev_b64 v[4:5], 11, v[4:5]
	v_lshl_add_u64 v[156:157], s[8:9], 0, v[4:5]
	v_add_co_u32_e32 v6, vcc, s62, v2
	v_lshl_add_u64 v[4:5], v[156:157], 0, v[152:153]
	s_nop 0
	v_addc_co_u32_e32 v7, vcc, 0, v3, vcc
	v_add_co_u32_e32 v8, vcc, s62, v4
	s_and_b32 s7, s42, 56
	v_lshrrev_b32_e32 v1, 2, v10
	s_or_b32 s6, s67, s6
	v_addc_co_u32_e32 v9, vcc, 0, v5, vcc
	v_and_b32_e32 v12, 12, v1
	s_movk_i32 s20, 0x1230
	s_or_b32 s84, s6, s7
	v_add_co_u32_e32 v60, vcc, s33, v4
	v_lshrrev_b32_e64 v12, v12, s20
	s_lshl_b64 s[6:7], s[84:85], 18
	v_addc_co_u32_e32 v61, vcc, 0, v5, vcc
	v_and_b32_e32 v11, 3, v10
	v_ashrrev_i32_e32 v1, 31, v0
	v_xor_b32_e32 v10, v12, v10
	s_add_u32 s6, s82, s6
	v_add_co_u32_e32 v62, vcc, s72, v4
	v_lshlrev_b32_e32 v13, 6, v0
	v_lshlrev_b64 v[0:1], 11, v[0:1]
	v_lshlrev_b32_e32 v10, 4, v10
	s_addc_u32 s7, s83, s7
	v_addc_co_u32_e32 v63, vcc, 0, v5, vcc
	s_nop 0
	v_readfirstlane_b32 s26, v2
	v_readfirstlane_b32 s27, v3
	v_readfirstlane_b32 s28, v4
	v_readfirstlane_b32 s29, v5
	v_lshrrev_b32_e32 v250, 6, v198
	s_nop 0
	v_readfirstlane_b32 s24, v250
	s_lshl_b32 s24, s24, 10
	v_lshrrev_b32_e32 v250, 2, v200
	v_lshrrev_b32_e32 v251, 4, v200
	v_lshlrev_b32_e32 v251, 2, v251
	v_mov_b32_e32 v248, 0x1230
	v_lshrrev_b32_e32 v251, v251, v248
	v_xor_b32_e32 v251, v251, v200
	v_and_b32_e32 v251, 3, v251
	v_lshlrev_b32_e32 v251, 4, v251
	v_lshl_add_u32 v244, v250, 11, v251
	v_add_u32_e32 v245, 0x20000, v244
	v_add_u32_e32 v246, 0x40000, v244
	v_add_u32_e32 v247, 0x60000, v244
	s_mov_b32 s25, 0
	s_add_u32 m0, s25, s24
	s_nop 0
	global_load_lds_dwordx4 v244, s[26:27]
	s_add_u32 m0, m0, 0x1000
	s_nop 0
	global_load_lds_dwordx4 v245, s[26:27]
	s_add_u32 m0, m0, 0x1000
	s_nop 0
	global_load_lds_dwordx4 v244, s[28:29]
	s_add_u32 m0, m0, 0x1000
	s_nop 0
	global_load_lds_dwordx4 v245, s[28:29]
	s_add_u32 m0, m0, 0x1000
	s_nop 0
	global_load_lds_dwordx4 v246, s[28:29]
	s_add_u32 m0, m0, 0x1000
	s_nop 0
	global_load_lds_dwordx4 v247, s[28:29]
	s_add_u32 s26, s26, 64
	s_addc_u32 s27, s27, 0
	s_add_u32 s28, s28, 64
	s_addc_u32 s29, s29, 0
	s_add_u32 s25, s25, 24576
	s_cmp_eq_u32 s25, 73728
	s_cselect_b32 s25, 0, s25
	s_add_u32 m0, s25, s24
	s_nop 0
	global_load_lds_dwordx4 v244, s[26:27]
	s_add_u32 m0, m0, 0x1000
	s_nop 0
	global_load_lds_dwordx4 v245, s[26:27]
	s_add_u32 m0, m0, 0x1000
	s_nop 0
	global_load_lds_dwordx4 v244, s[28:29]
	s_add_u32 m0, m0, 0x1000
	s_nop 0
	global_load_lds_dwordx4 v245, s[28:29]
	s_add_u32 m0, m0, 0x1000
	s_nop 0
	global_load_lds_dwordx4 v246, s[28:29]
	s_add_u32 m0, m0, 0x1000
	s_nop 0
	global_load_lds_dwordx4 v247, s[28:29]
	s_add_u32 s26, s26, 64
	s_addc_u32 s27, s27, 0
	s_add_u32 s28, s28, 64
	s_addc_u32 s29, s29, 0
	s_add_u32 s25, s25, 24576
	s_cmp_eq_u32 s25, 73728
	s_cselect_b32 s25, 0, s25
	s_add_u32 m0, s25, s24
	s_nop 0
	global_load_lds_dwordx4 v244, s[26:27]
	s_add_u32 m0, m0, 0x1000
	s_nop 0
	global_load_lds_dwordx4 v245, s[26:27]
	s_add_u32 m0, m0, 0x1000
	s_nop 0
	global_load_lds_dwordx4 v244, s[28:29]
	s_add_u32 m0, m0, 0x1000
	s_nop 0
	global_load_lds_dwordx4 v245, s[28:29]
	s_add_u32 m0, m0, 0x1000
	s_nop 0
	global_load_lds_dwordx4 v246, s[28:29]
	s_add_u32 m0, m0, 0x1000
	s_nop 0
	global_load_lds_dwordx4 v247, s[28:29]
	s_add_u32 s26, s26, 64
	s_addc_u32 s27, s27, 0
	s_add_u32 s28, s28, 64
	s_addc_u32 s29, s29, 0
	s_add_u32 s25, s25, 24576
	s_cmp_eq_u32 s25, 73728
	s_cselect_b32 s25, 0, s25
	v_mov_b32_e32 v24, 0
	v_mov_b32_e32 v25, v24
	v_mov_b32_e32 v26, v24
	v_mov_b32_e32 v27, v24
	v_mov_b32_e32 v28, v24
	v_mov_b32_e32 v29, v24
	v_mov_b32_e32 v30, v24
	v_mov_b32_e32 v31, v24
	v_mov_b32_e32 v32, v24
	v_mov_b32_e32 v33, v24
	v_mov_b32_e32 v34, v24
	v_mov_b32_e32 v35, v24
	v_mov_b32_e32 v64, v24
	v_mov_b32_e32 v65, v24
	v_mov_b32_e32 v66, v24
	v_mov_b32_e32 v67, v24
	v_mov_b32_e32 v68, v24
	v_mov_b32_e32 v69, v24
	v_mov_b32_e32 v70, v24
	v_mov_b32_e32 v71, v24
	v_mov_b32_e32 v60, v24
	v_mov_b32_e32 v61, v24
	v_mov_b32_e32 v62, v24
	v_mov_b32_e32 v63, v24
	v_mov_b32_e32 v100, v24
	v_mov_b32_e32 v101, v24
	v_mov_b32_e32 v102, v24
	v_mov_b32_e32 v103, v24
	v_mov_b32_e32 v104, v24
	v_mov_b32_e32 v105, v24
	v_mov_b32_e32 v106, v24
	v_mov_b32_e32 v107, v24
	v_mov_b32_e32 v120, v24
	v_mov_b32_e32 v121, v24
	v_mov_b32_e32 v122, v24
	v_mov_b32_e32 v36, v24
	v_mov_b32_e32 v37, v24
	v_mov_b32_e32 v38, v24
	v_mov_b32_e32 v39, v24
	v_mov_b32_e32 v52, v24
	v_mov_b32_e32 v53, v24
	v_mov_b32_e32 v54, v24
	v_mov_b32_e32 v55, v24
	v_mov_b32_e32 v56, v24
	v_mov_b32_e32 v57, v24
	v_mov_b32_e32 v58, v24
	v_mov_b32_e32 v59, v24
	v_mov_b32_e32 v40, v24
	v_mov_b32_e32 v41, v24
	v_mov_b32_e32 v42, v24
	v_mov_b32_e32 v43, v24
	v_mov_b32_e32 v44, v24
	v_mov_b32_e32 v45, v24
	v_mov_b32_e32 v46, v24
	v_mov_b32_e32 v47, v24
	v_mov_b32_e32 v48, v24
	v_mov_b32_e32 v49, v24
	v_mov_b32_e32 v50, v24
	v_mov_b32_e32 v51, v24
	v_mov_b32_e32 v123, v24
	v_mov_b32_e32 v128, v24
	v_mov_b32_e32 v129, v24
	v_mov_b32_e32 v130, v24
	v_mov_b32_e32 v131, v24
	v_mov_b32_e32 v108, v24
	v_mov_b32_e32 v109, v24
	v_mov_b32_e32 v110, v24
	v_mov_b32_e32 v111, v24
	v_mov_b32_e32 v112, v24
	v_mov_b32_e32 v113, v24
	v_mov_b32_e32 v114, v24
	v_mov_b32_e32 v115, v24
	v_mov_b32_e32 v116, v24
	v_mov_b32_e32 v117, v24
	v_mov_b32_e32 v118, v24
	v_mov_b32_e32 v119, v24
	v_mov_b32_e32 v124, v24
	v_mov_b32_e32 v125, v24
	v_mov_b32_e32 v126, v24
	v_mov_b32_e32 v127, v24
	v_mov_b32_e32 v80, v24
	v_mov_b32_e32 v81, v24
	v_mov_b32_e32 v82, v24
	v_mov_b32_e32 v83, v24
	v_mov_b32_e32 v88, v24
	v_mov_b32_e32 v89, v24
	v_mov_b32_e32 v90, v24
	v_mov_b32_e32 v91, v24
	v_mov_b32_e32 v92, v24
	v_mov_b32_e32 v93, v24
	v_mov_b32_e32 v94, v24
	v_mov_b32_e32 v95, v24
	v_mov_b32_e32 v76, v24
	v_mov_b32_e32 v77, v24
	v_mov_b32_e32 v78, v24
	v_mov_b32_e32 v79, v24
	v_mov_b32_e32 v132, v24
	v_mov_b32_e32 v133, v24
	v_mov_b32_e32 v134, v24
	v_mov_b32_e32 v135, v24
	v_mov_b32_e32 v136, v24
	v_mov_b32_e32 v137, v24
	v_mov_b32_e32 v138, v24
	v_mov_b32_e32 v139, v24
	v_mov_b32_e32 v140, v24
	v_mov_b32_e32 v141, v24
	v_mov_b32_e32 v142, v24
	v_mov_b32_e32 v143, v24
	v_mov_b32_e32 v144, v24
	v_mov_b32_e32 v145, v24
	v_mov_b32_e32 v146, v24
	v_mov_b32_e32 v147, v24
	v_mov_b32_e32 v96, v24
	v_mov_b32_e32 v97, v24
	v_mov_b32_e32 v98, v24
	v_mov_b32_e32 v99, v24
	v_mov_b32_e32 v84, v24
	v_mov_b32_e32 v85, v24
	v_mov_b32_e32 v86, v24
	v_mov_b32_e32 v87, v24
	v_mov_b32_e32 v72, v24
	v_mov_b32_e32 v73, v24
	v_mov_b32_e32 v74, v24
	v_mov_b32_e32 v75, v24
	v_mov_b32_e32 v148, v24
	v_mov_b32_e32 v149, v24
	v_mov_b32_e32 v150, v24
	v_mov_b32_e32 v151, v24
	s_waitcnt vmcnt(12)
	s_barrier
	s_mov_b32 s30, 0
	v_add_u32_e32 v248, s30, v155
	v_add_u32_e32 v249, s30, v160
	ds_read_b128 v[186:189], v248
	ds_read_b128 v[212:215], v249 offset:8192
	ds_read_b128 v[190:193], v248 offset:1024
	ds_read_b128 v[216:219], v249 offset:9216
	ds_read_b128 v[194:197], v248 offset:2048
	ds_read_b128 v[220:223], v249 offset:10240
	ds_read_b128 v[208:211], v248 offset:3072
	ds_read_b128 v[224:227], v249 offset:11264
	ds_read_b128 v[228:231], v249 offset:12288
	ds_read_b128 v[232:235], v249 offset:13312
	ds_read_b128 v[236:239], v249 offset:14336
	ds_read_b128 v[240:243], v249 offset:15360
	s_add_u32 s30, s30, 24576
	s_cmp_eq_u32 s30, 73728
	s_cselect_b32 s30, 0, s30
	s_waitcnt vmcnt(6)
	s_waitcnt lgkmcnt(0)
	s_barrier
	s_mov_b32 s31, 14
	s_cmpk_lt_u32 s37, 0x180
	s_cbranch_scc0 .Lgm3_cheap
